# P0 row rebalance: workgroups 0..127 (which also run the SSM discretisation) hand their 4th RMSNorm row per wave to workgroup bx+128
# speedup vs baseline: 1.0120x; 1.0120x over previous
.LBB0_115:
	s_add_i32 s30, s30, 1
	s_add_i32 s22, s22, s59
	s_cmp_eq_u32 s30, 6
	s_cbranch_scc1 .LBB0_135
	v_readlane_b32 s98, v248, 32
	s_nop 0
	s_cmp_lt_u32 s98, 0x80
	s_cbranch_scc1 .Lrow_low
	s_cmp_eq_u32 s30, 5
	s_cbranch_scc0 .LBB0_116
	s_mul_i32 s10, s59, 3
	s_add_i32 s10, s10, s66
	s_addk_i32 s10, 0xff80
	s_branch .LBB0_116
.Lrow_low:
	s_cmp_eq_u32 s30, 5
	s_cbranch_scc1 .LBB0_135
	s_cmp_eq_u32 s30, 3
	s_cbranch_scc0 .LBB0_116
	s_movk_i32 s10, 0x2410
